# lean hand-written initial raw-load issue for the first prep tile in both the early-prep phase and the attention role
# baseline (speedup 1.0000x reference)
.LBB0_275:
	s_and_b64 vcc, exec, s[24:25]
	s_cbranch_vccz .LBB0_1279
	s_cmpk_gt_i32 s30, 0x7f
	s_mov_b64 s[24:25], -1
	s_cbranch_scc0 .LBB0_1047
	s_add_i32 s80, s36, 0xffffff80
	s_cmpk_gt_u32 s30, 0x3bf
	s_cbranch_scc1 .LBB0_942
	s_add_i32 s38, s30, 0x80
	s_add_i32 s2, s30, 64
	s_lshr_b32 s2, s2, 3
	s_lshl_b32 s3, s38, 8
	s_and_b32 s3, s3, 0x300
	s_and_b32 s24, s30, 4
	s_sub_i32 s25, 0xff, s2
	s_cmp_eq_u32 s24, 0
	s_cselect_b32 s2, s2, s25
	s_or_b32 s2, s2, s3
	s_waitcnt vmcnt(0)
	v_mov_b32_e32 v4, v232
	s_lshl_b32 s31, s2, 4
	v_readlane_b32 s2, v252, 18
	v_readlane_b32 s3, v252, 19
	s_mul_i32 s26, s31, 0x900
	s_add_u32 s42, s2, s26
	s_addc_u32 s43, s3, 0
	s_sub_u32 s46, s42, 0x24000
	s_subb_u32 s47, s43, 0
	s_movk_i32 s49, 0x900
	s_mov_b32 s50, 0x38e38e39
	s_cmpk_lt_u32 s31, 0x4000
	s_cbranch_scc0 .Lpi0_ctx_att
	s_and_b32 s48, s31, 0xfff
	v_mov_b32_e32 v6, v232
	v_mul_hi_u32 v7, v6, s50
	v_lshrrev_b32_e32 v7, 6, v7
	v_mul_u32_u24_e32 v0, 0x120, v7
	v_sub_u32_e32 v6, v6, v0
	v_cmp_gt_u32_e32 vcc, 96, v6
	v_lshlrev_b32_e32 v0, 1, v6
	v_subrev_u32_e32 v2, 96, v6
	v_cndmask_b32_e32 v0, v2, v0, vcc
	v_mul_u32_u24_e32 v0, 0x556, v0
	v_lshrrev_b32_e32 v0, 16, v0
	v_and_b32_e32 v2, 1, v0
	v_lshl_add_u32 v2, v2, 1, -1
	v_lshrrev_b32_e32 v0, 1, v0
	v_mul_u32_u24_e32 v0, 6, v0
	v_lshlrev_b32_e32 v2, v0, v2
	v_lshlrev_b32_e64 v3, v0, 64
	v_add_u32_e32 v3, -1, v3
	v_mul_u32_u24_e32 v4, 0x900, v7
	v_lshl_add_u32 v4, v6, 3, v4
	global_load_dwordx2 v[58:59], v4, s[42:43]
	v_add_u32_e32 v5, 64, v2
	v_mad_u32_u24 v4, v5, s49, v4
	v_add_u32_e32 v5, s48, v7
	v_and_b32_e32 v5, v5, v3
	v_add_u32_e32 v5, v5, v2
	v_cmp_le_u32_e32 vcc, v5, v3
	v_mov_b32_e32 v60, 0
	v_mov_b32_e32 v61, 0
	s_and_saveexec_b64 s[24:25], vcc
	global_load_dwordx2 v[60:61], v4, s[46:47]
	s_mov_b64 exec, s[24:25]
	v_add_u32_e32 v6, 0x200, v232
	v_mul_hi_u32 v7, v6, s50
	v_lshrrev_b32_e32 v7, 6, v7
	v_mul_u32_u24_e32 v0, 0x120, v7
	v_sub_u32_e32 v6, v6, v0
	v_cmp_gt_u32_e32 vcc, 96, v6
	v_lshlrev_b32_e32 v0, 1, v6
	v_subrev_u32_e32 v2, 96, v6
	v_cndmask_b32_e32 v0, v2, v0, vcc
	v_mul_u32_u24_e32 v0, 0x556, v0
	v_lshrrev_b32_e32 v0, 16, v0
	v_and_b32_e32 v2, 1, v0
	v_lshl_add_u32 v2, v2, 1, -1
	v_lshrrev_b32_e32 v0, 1, v0
	v_mul_u32_u24_e32 v0, 6, v0
	v_lshlrev_b32_e32 v2, v0, v2
	v_lshlrev_b32_e64 v3, v0, 64
	v_add_u32_e32 v3, -1, v3
	v_mul_u32_u24_e32 v4, 0x900, v7
	v_lshl_add_u32 v4, v6, 3, v4
	global_load_dwordx2 v[62:63], v4, s[42:43]
	v_add_u32_e32 v5, 64, v2
	v_mad_u32_u24 v4, v5, s49, v4
	v_add_u32_e32 v5, s48, v7
	v_and_b32_e32 v5, v5, v3
	v_add_u32_e32 v5, v5, v2
	v_cmp_le_u32_e32 vcc, v5, v3
	v_mov_b32_e32 v64, 0
	v_mov_b32_e32 v65, 0
	s_and_saveexec_b64 s[24:25], vcc
	global_load_dwordx2 v[64:65], v4, s[46:47]
	s_mov_b64 exec, s[24:25]
	v_add_u32_e32 v6, 0x400, v232
	v_mul_hi_u32 v7, v6, s50
	v_lshrrev_b32_e32 v7, 6, v7
	v_mul_u32_u24_e32 v0, 0x120, v7
	v_sub_u32_e32 v6, v6, v0
	v_cmp_gt_u32_e32 vcc, 96, v6
	v_lshlrev_b32_e32 v0, 1, v6
	v_subrev_u32_e32 v2, 96, v6
	v_cndmask_b32_e32 v0, v2, v0, vcc
	v_mul_u32_u24_e32 v0, 0x556, v0
	v_lshrrev_b32_e32 v0, 16, v0
	v_and_b32_e32 v2, 1, v0
	v_lshl_add_u32 v2, v2, 1, -1
	v_lshrrev_b32_e32 v0, 1, v0
	v_mul_u32_u24_e32 v0, 6, v0
	v_lshlrev_b32_e32 v2, v0, v2
	v_lshlrev_b32_e64 v3, v0, 64
	v_add_u32_e32 v3, -1, v3
	v_mul_u32_u24_e32 v4, 0x900, v7
	v_lshl_add_u32 v4, v6, 3, v4
	global_load_dwordx2 v[66:67], v4, s[42:43]
	v_add_u32_e32 v5, 64, v2
	v_mad_u32_u24 v4, v5, s49, v4
	v_add_u32_e32 v5, s48, v7
	v_and_b32_e32 v5, v5, v3
	v_add_u32_e32 v5, v5, v2
	v_cmp_le_u32_e32 vcc, v5, v3
	v_mov_b32_e32 v68, 0
	v_mov_b32_e32 v69, 0
	s_and_saveexec_b64 s[24:25], vcc
	global_load_dwordx2 v[68:69], v4, s[46:47]
	s_mov_b64 exec, s[24:25]
	v_add_u32_e32 v6, 0x600, v232
	v_mul_hi_u32 v7, v6, s50
	v_lshrrev_b32_e32 v7, 6, v7
	v_mul_u32_u24_e32 v0, 0x120, v7
	v_sub_u32_e32 v6, v6, v0
	v_cmp_gt_u32_e32 vcc, 96, v6
	v_lshlrev_b32_e32 v0, 1, v6
	v_subrev_u32_e32 v2, 96, v6
	v_cndmask_b32_e32 v0, v2, v0, vcc
	v_mul_u32_u24_e32 v0, 0x556, v0
	v_lshrrev_b32_e32 v0, 16, v0
	v_and_b32_e32 v2, 1, v0
	v_lshl_add_u32 v2, v2, 1, -1
	v_lshrrev_b32_e32 v0, 1, v0
	v_mul_u32_u24_e32 v0, 6, v0
	v_lshlrev_b32_e32 v2, v0, v2
	v_lshlrev_b32_e64 v3, v0, 64
	v_add_u32_e32 v3, -1, v3
	v_mul_u32_u24_e32 v4, 0x900, v7
	v_lshl_add_u32 v4, v6, 3, v4
	global_load_dwordx2 v[70:71], v4, s[42:43]
	v_add_u32_e32 v5, 64, v2
	v_mad_u32_u24 v4, v5, s49, v4
	v_add_u32_e32 v5, s48, v7
	v_and_b32_e32 v5, v5, v3
	v_add_u32_e32 v5, v5, v2
	v_cmp_le_u32_e32 vcc, v5, v3
	v_mov_b32_e32 v72, 0
	v_mov_b32_e32 v73, 0
	s_and_saveexec_b64 s[24:25], vcc
	global_load_dwordx2 v[72:73], v4, s[46:47]
	s_mov_b64 exec, s[24:25]
	v_add_u32_e32 v6, 0x800, v232
	v_mul_hi_u32 v7, v6, s50
	v_lshrrev_b32_e32 v7, 6, v7
	v_mul_u32_u24_e32 v0, 0x120, v7
	v_sub_u32_e32 v6, v6, v0
	v_cmp_gt_u32_e32 vcc, 96, v6
	v_lshlrev_b32_e32 v0, 1, v6
	v_subrev_u32_e32 v2, 96, v6
	v_cndmask_b32_e32 v0, v2, v0, vcc
	v_mul_u32_u24_e32 v0, 0x556, v0
	v_lshrrev_b32_e32 v0, 16, v0
	v_and_b32_e32 v2, 1, v0
	v_lshl_add_u32 v2, v2, 1, -1
	v_lshrrev_b32_e32 v0, 1, v0
	v_mul_u32_u24_e32 v0, 6, v0
	v_lshlrev_b32_e32 v2, v0, v2
	v_lshlrev_b32_e64 v3, v0, 64
	v_add_u32_e32 v3, -1, v3
	v_mul_u32_u24_e32 v4, 0x900, v7
	v_lshl_add_u32 v4, v6, 3, v4
	global_load_dwordx2 v[74:75], v4, s[42:43]
	v_add_u32_e32 v5, 64, v2
	v_mad_u32_u24 v4, v5, s49, v4
	v_add_u32_e32 v5, s48, v7
	v_and_b32_e32 v5, v5, v3
	v_add_u32_e32 v5, v5, v2
	v_cmp_le_u32_e32 vcc, v5, v3
	v_mov_b32_e32 v76, 0
	v_mov_b32_e32 v77, 0
	s_and_saveexec_b64 s[24:25], vcc
	global_load_dwordx2 v[76:77], v4, s[46:47]
	s_mov_b64 exec, s[24:25]
	v_add_u32_e32 v6, 0xa00, v232
	v_mul_hi_u32 v7, v6, s50
	v_lshrrev_b32_e32 v7, 6, v7
	v_mul_u32_u24_e32 v0, 0x120, v7
	v_sub_u32_e32 v6, v6, v0
	v_cmp_gt_u32_e32 vcc, 96, v6
	v_lshlrev_b32_e32 v0, 1, v6
	v_subrev_u32_e32 v2, 96, v6
	v_cndmask_b32_e32 v0, v2, v0, vcc
	v_mul_u32_u24_e32 v0, 0x556, v0
	v_lshrrev_b32_e32 v0, 16, v0
	v_and_b32_e32 v2, 1, v0
	v_lshl_add_u32 v2, v2, 1, -1
	v_lshrrev_b32_e32 v0, 1, v0
	v_mul_u32_u24_e32 v0, 6, v0
	v_lshlrev_b32_e32 v2, v0, v2
	v_lshlrev_b32_e64 v3, v0, 64
	v_add_u32_e32 v3, -1, v3
	v_mul_u32_u24_e32 v4, 0x900, v7
	v_lshl_add_u32 v4, v6, 3, v4
	global_load_dwordx2 v[78:79], v4, s[42:43]
	v_add_u32_e32 v5, 64, v2
	v_mad_u32_u24 v4, v5, s49, v4
	v_add_u32_e32 v5, s48, v7
	v_and_b32_e32 v5, v5, v3
	v_add_u32_e32 v5, v5, v2
	v_cmp_le_u32_e32 vcc, v5, v3
	v_mov_b32_e32 v80, 0
	v_mov_b32_e32 v81, 0
	s_and_saveexec_b64 s[24:25], vcc
	global_load_dwordx2 v[80:81], v4, s[46:47]
	s_mov_b64 exec, s[24:25]
	v_add_u32_e32 v6, 0xc00, v232
	v_mul_hi_u32 v7, v6, s50
	v_lshrrev_b32_e32 v7, 6, v7
	v_mul_u32_u24_e32 v0, 0x120, v7
	v_sub_u32_e32 v6, v6, v0
	v_cmp_gt_u32_e32 vcc, 96, v6
	v_lshlrev_b32_e32 v0, 1, v6
	v_subrev_u32_e32 v2, 96, v6
	v_cndmask_b32_e32 v0, v2, v0, vcc
	v_mul_u32_u24_e32 v0, 0x556, v0
	v_lshrrev_b32_e32 v0, 16, v0
	v_and_b32_e32 v2, 1, v0
	v_lshl_add_u32 v2, v2, 1, -1
	v_lshrrev_b32_e32 v0, 1, v0
	v_mul_u32_u24_e32 v0, 6, v0
	v_lshlrev_b32_e32 v2, v0, v2
	v_lshlrev_b32_e64 v3, v0, 64
	v_add_u32_e32 v3, -1, v3
	v_mul_u32_u24_e32 v4, 0x900, v7
	v_lshl_add_u32 v4, v6, 3, v4
	global_load_dwordx2 v[82:83], v4, s[42:43]
	v_add_u32_e32 v5, 64, v2
	v_mad_u32_u24 v4, v5, s49, v4
	v_add_u32_e32 v5, s48, v7
	v_and_b32_e32 v5, v5, v3
	v_add_u32_e32 v5, v5, v2
	v_cmp_le_u32_e32 vcc, v5, v3
	v_mov_b32_e32 v84, 0
	v_mov_b32_e32 v85, 0
	s_and_saveexec_b64 s[24:25], vcc
	global_load_dwordx2 v[84:85], v4, s[46:47]
	s_mov_b64 exec, s[24:25]
	v_add_u32_e32 v6, 0xe00, v232
	v_mul_hi_u32 v7, v6, s50
	v_lshrrev_b32_e32 v7, 6, v7
	v_mul_u32_u24_e32 v0, 0x120, v7
	v_sub_u32_e32 v6, v6, v0
	v_cmp_gt_u32_e32 vcc, 96, v6
	v_lshlrev_b32_e32 v0, 1, v6
	v_subrev_u32_e32 v2, 96, v6
	v_cndmask_b32_e32 v0, v2, v0, vcc
	v_mul_u32_u24_e32 v0, 0x556, v0
	v_lshrrev_b32_e32 v0, 16, v0
	v_and_b32_e32 v2, 1, v0
	v_lshl_add_u32 v2, v2, 1, -1
	v_lshrrev_b32_e32 v0, 1, v0
	v_mul_u32_u24_e32 v0, 6, v0
	v_lshlrev_b32_e32 v2, v0, v2
	v_lshlrev_b32_e64 v3, v0, 64
	v_add_u32_e32 v3, -1, v3
	v_mul_u32_u24_e32 v4, 0x900, v7
	v_lshl_add_u32 v4, v6, 3, v4
	global_load_dwordx2 v[86:87], v4, s[42:43]
	v_add_u32_e32 v5, 64, v2
	v_mad_u32_u24 v4, v5, s49, v4
	v_add_u32_e32 v5, s48, v7
	v_and_b32_e32 v5, v5, v3
	v_add_u32_e32 v5, v5, v2
	v_cmp_le_u32_e32 vcc, v5, v3
	v_mov_b32_e32 v88, 0
	v_mov_b32_e32 v89, 0
	s_and_saveexec_b64 s[24:25], vcc
	global_load_dwordx2 v[88:89], v4, s[46:47]
	s_mov_b64 exec, s[24:25]
	v_add_u32_e32 v6, 0x1000, v232
	v_mul_hi_u32 v7, v6, s50
	v_lshrrev_b32_e32 v7, 6, v7
	v_mul_u32_u24_e32 v0, 0x120, v7
	v_sub_u32_e32 v6, v6, v0
	v_cmp_gt_u32_e32 vcc, 96, v6
	v_lshlrev_b32_e32 v0, 1, v6
	v_subrev_u32_e32 v2, 96, v6
	v_cndmask_b32_e32 v0, v2, v0, vcc
	v_mul_u32_u24_e32 v0, 0x556, v0
	v_lshrrev_b32_e32 v0, 16, v0
	v_and_b32_e32 v2, 1, v0
	v_lshl_add_u32 v2, v2, 1, -1
	v_lshrrev_b32_e32 v0, 1, v0
	v_mul_u32_u24_e32 v0, 6, v0
	v_lshlrev_b32_e32 v2, v0, v2
	v_lshlrev_b32_e64 v3, v0, 64
	v_add_u32_e32 v3, -1, v3
	v_mul_u32_u24_e32 v4, 0x900, v7
	v_lshl_add_u32 v4, v6, 3, v4
	global_load_dwordx2 v[90:91], v4, s[42:43]
	v_add_u32_e32 v5, 64, v2
	v_mad_u32_u24 v4, v5, s49, v4
	v_add_u32_e32 v5, s48, v7
	v_and_b32_e32 v5, v5, v3
	v_add_u32_e32 v5, v5, v2
	v_cmp_le_u32_e32 vcc, v5, v3
	v_mov_b32_e32 v92, 0
	v_mov_b32_e32 v93, 0
	s_and_saveexec_b64 s[24:25], vcc
	global_load_dwordx2 v[92:93], v4, s[46:47]
	s_mov_b64 exec, s[24:25]
	s_branch .Lpi0_done_att
.Lpi0_ctx_att:
	s_and_b32 s48, s31, 0xff
	v_mov_b32_e32 v6, v232
	v_mul_hi_u32 v7, v6, s50
	v_lshrrev_b32_e32 v7, 6, v7
	v_mul_u32_u24_e32 v0, 0x120, v7
	v_sub_u32_e32 v6, v6, v0
	v_cmp_gt_u32_e32 vcc, 96, v6
	v_lshlrev_b32_e32 v0, 1, v6
	v_subrev_u32_e32 v2, 96, v6
	v_cndmask_b32_e32 v0, v2, v0, vcc
	v_cmp_lt_u32_e32 vcc, 0x5f, v0
	v_cndmask_b32_e64 v2, -1, 1, vcc
	v_mul_u32_u24_e32 v4, 0x900, v7
	v_lshl_add_u32 v4, v6, 3, v4
	global_load_dwordx2 v[58:59], v4, s[42:43]
	v_add_u32_e32 v5, 64, v2
	v_mad_u32_u24 v4, v5, s49, v4
	v_add_u32_e32 v5, s48, v7
	v_add_u32_e32 v5, v5, v2
	v_cmp_gt_u32_e32 vcc, 0x100, v5
	v_mov_b32_e32 v60, 0
	v_mov_b32_e32 v61, 0
	s_and_saveexec_b64 s[24:25], vcc
	global_load_dwordx2 v[60:61], v4, s[46:47]
	s_mov_b64 exec, s[24:25]
	v_add_u32_e32 v6, 0x200, v232
	v_mul_hi_u32 v7, v6, s50
	v_lshrrev_b32_e32 v7, 6, v7
	v_mul_u32_u24_e32 v0, 0x120, v7
	v_sub_u32_e32 v6, v6, v0
	v_cmp_gt_u32_e32 vcc, 96, v6
	v_lshlrev_b32_e32 v0, 1, v6
	v_subrev_u32_e32 v2, 96, v6
	v_cndmask_b32_e32 v0, v2, v0, vcc
	v_cmp_lt_u32_e32 vcc, 0x5f, v0
	v_cndmask_b32_e64 v2, -1, 1, vcc
	v_mul_u32_u24_e32 v4, 0x900, v7
	v_lshl_add_u32 v4, v6, 3, v4
	global_load_dwordx2 v[62:63], v4, s[42:43]
	v_add_u32_e32 v5, 64, v2
	v_mad_u32_u24 v4, v5, s49, v4
	v_add_u32_e32 v5, s48, v7
	v_add_u32_e32 v5, v5, v2
	v_cmp_gt_u32_e32 vcc, 0x100, v5
	v_mov_b32_e32 v64, 0
	v_mov_b32_e32 v65, 0
	s_and_saveexec_b64 s[24:25], vcc
	global_load_dwordx2 v[64:65], v4, s[46:47]
	s_mov_b64 exec, s[24:25]
	v_add_u32_e32 v6, 0x400, v232
	v_mul_hi_u32 v7, v6, s50
	v_lshrrev_b32_e32 v7, 6, v7
	v_mul_u32_u24_e32 v0, 0x120, v7
	v_sub_u32_e32 v6, v6, v0
	v_cmp_gt_u32_e32 vcc, 96, v6
	v_lshlrev_b32_e32 v0, 1, v6
	v_subrev_u32_e32 v2, 96, v6
	v_cndmask_b32_e32 v0, v2, v0, vcc
	v_cmp_lt_u32_e32 vcc, 0x5f, v0
	v_cndmask_b32_e64 v2, -1, 1, vcc
	v_mul_u32_u24_e32 v4, 0x900, v7
	v_lshl_add_u32 v4, v6, 3, v4
	global_load_dwordx2 v[66:67], v4, s[42:43]
	v_add_u32_e32 v5, 64, v2
	v_mad_u32_u24 v4, v5, s49, v4
	v_add_u32_e32 v5, s48, v7
	v_add_u32_e32 v5, v5, v2
	v_cmp_gt_u32_e32 vcc, 0x100, v5
	v_mov_b32_e32 v68, 0
	v_mov_b32_e32 v69, 0
	s_and_saveexec_b64 s[24:25], vcc
	global_load_dwordx2 v[68:69], v4, s[46:47]
	s_mov_b64 exec, s[24:25]
	v_add_u32_e32 v6, 0x600, v232
	v_mul_hi_u32 v7, v6, s50
	v_lshrrev_b32_e32 v7, 6, v7
	v_mul_u32_u24_e32 v0, 0x120, v7
	v_sub_u32_e32 v6, v6, v0
	v_cmp_gt_u32_e32 vcc, 96, v6
	v_lshlrev_b32_e32 v0, 1, v6
	v_subrev_u32_e32 v2, 96, v6
	v_cndmask_b32_e32 v0, v2, v0, vcc
	v_cmp_lt_u32_e32 vcc, 0x5f, v0
	v_cndmask_b32_e64 v2, -1, 1, vcc
	v_mul_u32_u24_e32 v4, 0x900, v7
	v_lshl_add_u32 v4, v6, 3, v4
	global_load_dwordx2 v[70:71], v4, s[42:43]
	v_add_u32_e32 v5, 64, v2
	v_mad_u32_u24 v4, v5, s49, v4
	v_add_u32_e32 v5, s48, v7
	v_add_u32_e32 v5, v5, v2
	v_cmp_gt_u32_e32 vcc, 0x100, v5
	v_mov_b32_e32 v72, 0
	v_mov_b32_e32 v73, 0
	s_and_saveexec_b64 s[24:25], vcc
	global_load_dwordx2 v[72:73], v4, s[46:47]
	s_mov_b64 exec, s[24:25]
	v_add_u32_e32 v6, 0x800, v232
	v_mul_hi_u32 v7, v6, s50
	v_lshrrev_b32_e32 v7, 6, v7
	v_mul_u32_u24_e32 v0, 0x120, v7
	v_sub_u32_e32 v6, v6, v0
	v_cmp_gt_u32_e32 vcc, 96, v6
	v_lshlrev_b32_e32 v0, 1, v6
	v_subrev_u32_e32 v2, 96, v6
	v_cndmask_b32_e32 v0, v2, v0, vcc
	v_cmp_lt_u32_e32 vcc, 0x5f, v0
	v_cndmask_b32_e64 v2, -1, 1, vcc
	v_mul_u32_u24_e32 v4, 0x900, v7
	v_lshl_add_u32 v4, v6, 3, v4
	global_load_dwordx2 v[74:75], v4, s[42:43]
	v_add_u32_e32 v5, 64, v2
	v_mad_u32_u24 v4, v5, s49, v4
	v_add_u32_e32 v5, s48, v7
	v_add_u32_e32 v5, v5, v2
	v_cmp_gt_u32_e32 vcc, 0x100, v5
	v_mov_b32_e32 v76, 0
	v_mov_b32_e32 v77, 0
	s_and_saveexec_b64 s[24:25], vcc
	global_load_dwordx2 v[76:77], v4, s[46:47]
	s_mov_b64 exec, s[24:25]
	v_add_u32_e32 v6, 0xa00, v232
	v_mul_hi_u32 v7, v6, s50
	v_lshrrev_b32_e32 v7, 6, v7
	v_mul_u32_u24_e32 v0, 0x120, v7
	v_sub_u32_e32 v6, v6, v0
	v_cmp_gt_u32_e32 vcc, 96, v6
	v_lshlrev_b32_e32 v0, 1, v6
	v_subrev_u32_e32 v2, 96, v6
	v_cndmask_b32_e32 v0, v2, v0, vcc
	v_cmp_lt_u32_e32 vcc, 0x5f, v0
	v_cndmask_b32_e64 v2, -1, 1, vcc
	v_mul_u32_u24_e32 v4, 0x900, v7
	v_lshl_add_u32 v4, v6, 3, v4
	global_load_dwordx2 v[78:79], v4, s[42:43]
	v_add_u32_e32 v5, 64, v2
	v_mad_u32_u24 v4, v5, s49, v4
	v_add_u32_e32 v5, s48, v7
	v_add_u32_e32 v5, v5, v2
	v_cmp_gt_u32_e32 vcc, 0x100, v5
	v_mov_b32_e32 v80, 0
	v_mov_b32_e32 v81, 0
	s_and_saveexec_b64 s[24:25], vcc
	global_load_dwordx2 v[80:81], v4, s[46:47]
	s_mov_b64 exec, s[24:25]
	v_add_u32_e32 v6, 0xc00, v232
	v_mul_hi_u32 v7, v6, s50
	v_lshrrev_b32_e32 v7, 6, v7
	v_mul_u32_u24_e32 v0, 0x120, v7
	v_sub_u32_e32 v6, v6, v0
	v_cmp_gt_u32_e32 vcc, 96, v6
	v_lshlrev_b32_e32 v0, 1, v6
	v_subrev_u32_e32 v2, 96, v6
	v_cndmask_b32_e32 v0, v2, v0, vcc
	v_cmp_lt_u32_e32 vcc, 0x5f, v0
	v_cndmask_b32_e64 v2, -1, 1, vcc
	v_mul_u32_u24_e32 v4, 0x900, v7
	v_lshl_add_u32 v4, v6, 3, v4
	global_load_dwordx2 v[82:83], v4, s[42:43]
	v_add_u32_e32 v5, 64, v2
	v_mad_u32_u24 v4, v5, s49, v4
	v_add_u32_e32 v5, s48, v7
	v_add_u32_e32 v5, v5, v2
	v_cmp_gt_u32_e32 vcc, 0x100, v5
	v_mov_b32_e32 v84, 0
	v_mov_b32_e32 v85, 0
	s_and_saveexec_b64 s[24:25], vcc
	global_load_dwordx2 v[84:85], v4, s[46:47]
	s_mov_b64 exec, s[24:25]
	v_add_u32_e32 v6, 0xe00, v232
	v_mul_hi_u32 v7, v6, s50
	v_lshrrev_b32_e32 v7, 6, v7
	v_mul_u32_u24_e32 v0, 0x120, v7
	v_sub_u32_e32 v6, v6, v0
	v_cmp_gt_u32_e32 vcc, 96, v6
	v_lshlrev_b32_e32 v0, 1, v6
	v_subrev_u32_e32 v2, 96, v6
	v_cndmask_b32_e32 v0, v2, v0, vcc
	v_cmp_lt_u32_e32 vcc, 0x5f, v0
	v_cndmask_b32_e64 v2, -1, 1, vcc
	v_mul_u32_u24_e32 v4, 0x900, v7
	v_lshl_add_u32 v4, v6, 3, v4
	global_load_dwordx2 v[86:87], v4, s[42:43]
	v_add_u32_e32 v5, 64, v2
	v_mad_u32_u24 v4, v5, s49, v4
	v_add_u32_e32 v5, s48, v7
	v_add_u32_e32 v5, v5, v2
	v_cmp_gt_u32_e32 vcc, 0x100, v5
	v_mov_b32_e32 v88, 0
	v_mov_b32_e32 v89, 0
	s_and_saveexec_b64 s[24:25], vcc
	global_load_dwordx2 v[88:89], v4, s[46:47]
	s_mov_b64 exec, s[24:25]
	v_add_u32_e32 v6, 0x1000, v232
	v_mul_hi_u32 v7, v6, s50
	v_lshrrev_b32_e32 v7, 6, v7
	v_mul_u32_u24_e32 v0, 0x120, v7
	v_sub_u32_e32 v6, v6, v0
	v_cmp_gt_u32_e32 vcc, 96, v6
	v_lshlrev_b32_e32 v0, 1, v6
	v_subrev_u32_e32 v2, 96, v6
	v_cndmask_b32_e32 v0, v2, v0, vcc
	v_cmp_lt_u32_e32 vcc, 0x5f, v0
	v_cndmask_b32_e64 v2, -1, 1, vcc
	v_mul_u32_u24_e32 v4, 0x900, v7
	v_lshl_add_u32 v4, v6, 3, v4
	global_load_dwordx2 v[90:91], v4, s[42:43]
	v_add_u32_e32 v5, 64, v2
	v_mad_u32_u24 v4, v5, s49, v4
	v_add_u32_e32 v5, s48, v7
	v_add_u32_e32 v5, v5, v2
	v_cmp_gt_u32_e32 vcc, 0x100, v5
	v_mov_b32_e32 v92, 0
	v_mov_b32_e32 v93, 0
	s_and_saveexec_b64 s[24:25], vcc
	global_load_dwordx2 v[92:93], v4, s[46:47]
	s_mov_b64 exec, s[24:25]
.Lpi0_done_att:
	s_abs_i32 s37, s80
	v_cvt_f32_u32_e32 v0, s37
	s_ashr_i32 s2, s80, 31
	v_writelane_b32 v249, s2, 36
	s_sub_i32 s2, 0, s37
	v_rcp_iflag_f32_e32 v0, v0
	s_nop 0
	v_mul_f32_e32 v0, 0x4f7ffffe, v0
	v_cvt_u32_f32_e32 v0, v0
	s_nop 0
	v_readfirstlane_b32 s3, v0
	s_mul_i32 s2, s2, s3
	s_mul_hi_u32 s2, s3, s2
	s_add_i32 s2, s3, s2
	v_writelane_b32 v249, s2, 37
	s_branch .LBB0_532

.LBB0_1287:
	s_waitcnt vmcnt(0)
	v_mov_b32_e32 v4, v232
	s_lshl_b32 s31, s26, 4
	v_readlane_b32 s2, v252, 18
	v_readlane_b32 s3, v252, 19
	s_mul_i32 s26, s31, 0x900
	s_add_u32 s42, s2, s26
	s_addc_u32 s43, s3, 0
	s_sub_u32 s46, s42, 0x24000
	s_subb_u32 s47, s43, 0
	s_movk_i32 s49, 0x900
	s_mov_b32 s50, 0x38e38e39
	s_cmpk_lt_u32 s31, 0x4000
	s_cbranch_scc0 .Lpi0_ctx_early
	s_and_b32 s48, s31, 0xfff
	v_mov_b32_e32 v6, v232
	v_mul_hi_u32 v7, v6, s50
	v_lshrrev_b32_e32 v7, 6, v7
	v_mul_u32_u24_e32 v0, 0x120, v7
	v_sub_u32_e32 v6, v6, v0
	v_cmp_gt_u32_e32 vcc, 96, v6
	v_lshlrev_b32_e32 v0, 1, v6
	v_subrev_u32_e32 v2, 96, v6
	v_cndmask_b32_e32 v0, v2, v0, vcc
	v_mul_u32_u24_e32 v0, 0x556, v0
	v_lshrrev_b32_e32 v0, 16, v0
	v_and_b32_e32 v2, 1, v0
	v_lshl_add_u32 v2, v2, 1, -1
	v_lshrrev_b32_e32 v0, 1, v0
	v_mul_u32_u24_e32 v0, 6, v0
	v_lshlrev_b32_e32 v2, v0, v2
	v_lshlrev_b32_e64 v3, v0, 64
	v_add_u32_e32 v3, -1, v3
	v_mul_u32_u24_e32 v4, 0x900, v7
	v_lshl_add_u32 v4, v6, 3, v4
	global_load_dwordx2 v[58:59], v4, s[42:43]
	v_add_u32_e32 v5, 64, v2
	v_mad_u32_u24 v4, v5, s49, v4
	v_add_u32_e32 v5, s48, v7
	v_and_b32_e32 v5, v5, v3
	v_add_u32_e32 v5, v5, v2
	v_cmp_le_u32_e32 vcc, v5, v3
	v_mov_b32_e32 v60, 0
	v_mov_b32_e32 v61, 0
	s_and_saveexec_b64 s[24:25], vcc
	global_load_dwordx2 v[60:61], v4, s[46:47]
	s_mov_b64 exec, s[24:25]
	v_add_u32_e32 v6, 0x200, v232
	v_mul_hi_u32 v7, v6, s50
	v_lshrrev_b32_e32 v7, 6, v7
	v_mul_u32_u24_e32 v0, 0x120, v7
	v_sub_u32_e32 v6, v6, v0
	v_cmp_gt_u32_e32 vcc, 96, v6
	v_lshlrev_b32_e32 v0, 1, v6
	v_subrev_u32_e32 v2, 96, v6
	v_cndmask_b32_e32 v0, v2, v0, vcc
	v_mul_u32_u24_e32 v0, 0x556, v0
	v_lshrrev_b32_e32 v0, 16, v0
	v_and_b32_e32 v2, 1, v0
	v_lshl_add_u32 v2, v2, 1, -1
	v_lshrrev_b32_e32 v0, 1, v0
	v_mul_u32_u24_e32 v0, 6, v0
	v_lshlrev_b32_e32 v2, v0, v2
	v_lshlrev_b32_e64 v3, v0, 64
	v_add_u32_e32 v3, -1, v3
	v_mul_u32_u24_e32 v4, 0x900, v7
	v_lshl_add_u32 v4, v6, 3, v4
	global_load_dwordx2 v[62:63], v4, s[42:43]
	v_add_u32_e32 v5, 64, v2
	v_mad_u32_u24 v4, v5, s49, v4
	v_add_u32_e32 v5, s48, v7
	v_and_b32_e32 v5, v5, v3
	v_add_u32_e32 v5, v5, v2
	v_cmp_le_u32_e32 vcc, v5, v3
	v_mov_b32_e32 v64, 0
	v_mov_b32_e32 v65, 0
	s_and_saveexec_b64 s[24:25], vcc
	global_load_dwordx2 v[64:65], v4, s[46:47]
	s_mov_b64 exec, s[24:25]
	v_add_u32_e32 v6, 0x400, v232
	v_mul_hi_u32 v7, v6, s50
	v_lshrrev_b32_e32 v7, 6, v7
	v_mul_u32_u24_e32 v0, 0x120, v7
	v_sub_u32_e32 v6, v6, v0
	v_cmp_gt_u32_e32 vcc, 96, v6
	v_lshlrev_b32_e32 v0, 1, v6
	v_subrev_u32_e32 v2, 96, v6
	v_cndmask_b32_e32 v0, v2, v0, vcc
	v_mul_u32_u24_e32 v0, 0x556, v0
	v_lshrrev_b32_e32 v0, 16, v0
	v_and_b32_e32 v2, 1, v0
	v_lshl_add_u32 v2, v2, 1, -1
	v_lshrrev_b32_e32 v0, 1, v0
	v_mul_u32_u24_e32 v0, 6, v0
	v_lshlrev_b32_e32 v2, v0, v2
	v_lshlrev_b32_e64 v3, v0, 64
	v_add_u32_e32 v3, -1, v3
	v_mul_u32_u24_e32 v4, 0x900, v7
	v_lshl_add_u32 v4, v6, 3, v4
	global_load_dwordx2 v[66:67], v4, s[42:43]
	v_add_u32_e32 v5, 64, v2
	v_mad_u32_u24 v4, v5, s49, v4
	v_add_u32_e32 v5, s48, v7
	v_and_b32_e32 v5, v5, v3
	v_add_u32_e32 v5, v5, v2
	v_cmp_le_u32_e32 vcc, v5, v3
	v_mov_b32_e32 v68, 0
	v_mov_b32_e32 v69, 0
	s_and_saveexec_b64 s[24:25], vcc
	global_load_dwordx2 v[68:69], v4, s[46:47]
	s_mov_b64 exec, s[24:25]
	v_add_u32_e32 v6, 0x600, v232
	v_mul_hi_u32 v7, v6, s50
	v_lshrrev_b32_e32 v7, 6, v7
	v_mul_u32_u24_e32 v0, 0x120, v7
	v_sub_u32_e32 v6, v6, v0
	v_cmp_gt_u32_e32 vcc, 96, v6
	v_lshlrev_b32_e32 v0, 1, v6
	v_subrev_u32_e32 v2, 96, v6
	v_cndmask_b32_e32 v0, v2, v0, vcc
	v_mul_u32_u24_e32 v0, 0x556, v0
	v_lshrrev_b32_e32 v0, 16, v0
	v_and_b32_e32 v2, 1, v0
	v_lshl_add_u32 v2, v2, 1, -1
	v_lshrrev_b32_e32 v0, 1, v0
	v_mul_u32_u24_e32 v0, 6, v0
	v_lshlrev_b32_e32 v2, v0, v2
	v_lshlrev_b32_e64 v3, v0, 64
	v_add_u32_e32 v3, -1, v3
	v_mul_u32_u24_e32 v4, 0x900, v7
	v_lshl_add_u32 v4, v6, 3, v4
	global_load_dwordx2 v[70:71], v4, s[42:43]
	v_add_u32_e32 v5, 64, v2
	v_mad_u32_u24 v4, v5, s49, v4
	v_add_u32_e32 v5, s48, v7
	v_and_b32_e32 v5, v5, v3
	v_add_u32_e32 v5, v5, v2
	v_cmp_le_u32_e32 vcc, v5, v3
	v_mov_b32_e32 v72, 0
	v_mov_b32_e32 v73, 0
	s_and_saveexec_b64 s[24:25], vcc
	global_load_dwordx2 v[72:73], v4, s[46:47]
	s_mov_b64 exec, s[24:25]
	v_add_u32_e32 v6, 0x800, v232
	v_mul_hi_u32 v7, v6, s50
	v_lshrrev_b32_e32 v7, 6, v7
	v_mul_u32_u24_e32 v0, 0x120, v7
	v_sub_u32_e32 v6, v6, v0
	v_cmp_gt_u32_e32 vcc, 96, v6
	v_lshlrev_b32_e32 v0, 1, v6
	v_subrev_u32_e32 v2, 96, v6
	v_cndmask_b32_e32 v0, v2, v0, vcc
	v_mul_u32_u24_e32 v0, 0x556, v0
	v_lshrrev_b32_e32 v0, 16, v0
	v_and_b32_e32 v2, 1, v0
	v_lshl_add_u32 v2, v2, 1, -1
	v_lshrrev_b32_e32 v0, 1, v0
	v_mul_u32_u24_e32 v0, 6, v0
	v_lshlrev_b32_e32 v2, v0, v2
	v_lshlrev_b32_e64 v3, v0, 64
	v_add_u32_e32 v3, -1, v3
	v_mul_u32_u24_e32 v4, 0x900, v7
	v_lshl_add_u32 v4, v6, 3, v4
	global_load_dwordx2 v[74:75], v4, s[42:43]
	v_add_u32_e32 v5, 64, v2
	v_mad_u32_u24 v4, v5, s49, v4
	v_add_u32_e32 v5, s48, v7
	v_and_b32_e32 v5, v5, v3
	v_add_u32_e32 v5, v5, v2
	v_cmp_le_u32_e32 vcc, v5, v3
	v_mov_b32_e32 v76, 0
	v_mov_b32_e32 v77, 0
	s_and_saveexec_b64 s[24:25], vcc
	global_load_dwordx2 v[76:77], v4, s[46:47]
	s_mov_b64 exec, s[24:25]
	v_add_u32_e32 v6, 0xa00, v232
	v_mul_hi_u32 v7, v6, s50
	v_lshrrev_b32_e32 v7, 6, v7
	v_mul_u32_u24_e32 v0, 0x120, v7
	v_sub_u32_e32 v6, v6, v0
	v_cmp_gt_u32_e32 vcc, 96, v6
	v_lshlrev_b32_e32 v0, 1, v6
	v_subrev_u32_e32 v2, 96, v6
	v_cndmask_b32_e32 v0, v2, v0, vcc
	v_mul_u32_u24_e32 v0, 0x556, v0
	v_lshrrev_b32_e32 v0, 16, v0
	v_and_b32_e32 v2, 1, v0
	v_lshl_add_u32 v2, v2, 1, -1
	v_lshrrev_b32_e32 v0, 1, v0
	v_mul_u32_u24_e32 v0, 6, v0
	v_lshlrev_b32_e32 v2, v0, v2
	v_lshlrev_b32_e64 v3, v0, 64
	v_add_u32_e32 v3, -1, v3
	v_mul_u32_u24_e32 v4, 0x900, v7
	v_lshl_add_u32 v4, v6, 3, v4
	global_load_dwordx2 v[78:79], v4, s[42:43]
	v_add_u32_e32 v5, 64, v2
	v_mad_u32_u24 v4, v5, s49, v4
	v_add_u32_e32 v5, s48, v7
	v_and_b32_e32 v5, v5, v3
	v_add_u32_e32 v5, v5, v2
	v_cmp_le_u32_e32 vcc, v5, v3
	v_mov_b32_e32 v80, 0
	v_mov_b32_e32 v81, 0
	s_and_saveexec_b64 s[24:25], vcc
	global_load_dwordx2 v[80:81], v4, s[46:47]
	s_mov_b64 exec, s[24:25]
	v_add_u32_e32 v6, 0xc00, v232
	v_mul_hi_u32 v7, v6, s50
	v_lshrrev_b32_e32 v7, 6, v7
	v_mul_u32_u24_e32 v0, 0x120, v7
	v_sub_u32_e32 v6, v6, v0
	v_cmp_gt_u32_e32 vcc, 96, v6
	v_lshlrev_b32_e32 v0, 1, v6
	v_subrev_u32_e32 v2, 96, v6
	v_cndmask_b32_e32 v0, v2, v0, vcc
	v_mul_u32_u24_e32 v0, 0x556, v0
	v_lshrrev_b32_e32 v0, 16, v0
	v_and_b32_e32 v2, 1, v0
	v_lshl_add_u32 v2, v2, 1, -1
	v_lshrrev_b32_e32 v0, 1, v0
	v_mul_u32_u24_e32 v0, 6, v0
	v_lshlrev_b32_e32 v2, v0, v2
	v_lshlrev_b32_e64 v3, v0, 64
	v_add_u32_e32 v3, -1, v3
	v_mul_u32_u24_e32 v4, 0x900, v7
	v_lshl_add_u32 v4, v6, 3, v4
	global_load_dwordx2 v[82:83], v4, s[42:43]
	v_add_u32_e32 v5, 64, v2
	v_mad_u32_u24 v4, v5, s49, v4
	v_add_u32_e32 v5, s48, v7
	v_and_b32_e32 v5, v5, v3
	v_add_u32_e32 v5, v5, v2
	v_cmp_le_u32_e32 vcc, v5, v3
	v_mov_b32_e32 v84, 0
	v_mov_b32_e32 v85, 0
	s_and_saveexec_b64 s[24:25], vcc
	global_load_dwordx2 v[84:85], v4, s[46:47]
	s_mov_b64 exec, s[24:25]
	v_add_u32_e32 v6, 0xe00, v232
	v_mul_hi_u32 v7, v6, s50
	v_lshrrev_b32_e32 v7, 6, v7
	v_mul_u32_u24_e32 v0, 0x120, v7
	v_sub_u32_e32 v6, v6, v0
	v_cmp_gt_u32_e32 vcc, 96, v6
	v_lshlrev_b32_e32 v0, 1, v6
	v_subrev_u32_e32 v2, 96, v6
	v_cndmask_b32_e32 v0, v2, v0, vcc
	v_mul_u32_u24_e32 v0, 0x556, v0
	v_lshrrev_b32_e32 v0, 16, v0
	v_and_b32_e32 v2, 1, v0
	v_lshl_add_u32 v2, v2, 1, -1
	v_lshrrev_b32_e32 v0, 1, v0
	v_mul_u32_u24_e32 v0, 6, v0
	v_lshlrev_b32_e32 v2, v0, v2
	v_lshlrev_b32_e64 v3, v0, 64
	v_add_u32_e32 v3, -1, v3
	v_mul_u32_u24_e32 v4, 0x900, v7
	v_lshl_add_u32 v4, v6, 3, v4
	global_load_dwordx2 v[86:87], v4, s[42:43]
	v_add_u32_e32 v5, 64, v2
	v_mad_u32_u24 v4, v5, s49, v4
	v_add_u32_e32 v5, s48, v7
	v_and_b32_e32 v5, v5, v3
	v_add_u32_e32 v5, v5, v2
	v_cmp_le_u32_e32 vcc, v5, v3
	v_mov_b32_e32 v88, 0
	v_mov_b32_e32 v89, 0
	s_and_saveexec_b64 s[24:25], vcc
	global_load_dwordx2 v[88:89], v4, s[46:47]
	s_mov_b64 exec, s[24:25]
	v_add_u32_e32 v6, 0x1000, v232
	v_mul_hi_u32 v7, v6, s50
	v_lshrrev_b32_e32 v7, 6, v7
	v_mul_u32_u24_e32 v0, 0x120, v7
	v_sub_u32_e32 v6, v6, v0
	v_cmp_gt_u32_e32 vcc, 96, v6
	v_lshlrev_b32_e32 v0, 1, v6
	v_subrev_u32_e32 v2, 96, v6
	v_cndmask_b32_e32 v0, v2, v0, vcc
	v_mul_u32_u24_e32 v0, 0x556, v0
	v_lshrrev_b32_e32 v0, 16, v0
	v_and_b32_e32 v2, 1, v0
	v_lshl_add_u32 v2, v2, 1, -1
	v_lshrrev_b32_e32 v0, 1, v0
	v_mul_u32_u24_e32 v0, 6, v0
	v_lshlrev_b32_e32 v2, v0, v2
	v_lshlrev_b32_e64 v3, v0, 64
	v_add_u32_e32 v3, -1, v3
	v_mul_u32_u24_e32 v4, 0x900, v7
	v_lshl_add_u32 v4, v6, 3, v4
	global_load_dwordx2 v[90:91], v4, s[42:43]
	v_add_u32_e32 v5, 64, v2
	v_mad_u32_u24 v4, v5, s49, v4
	v_add_u32_e32 v5, s48, v7
	v_and_b32_e32 v5, v5, v3
	v_add_u32_e32 v5, v5, v2
	v_cmp_le_u32_e32 vcc, v5, v3
	v_mov_b32_e32 v92, 0
	v_mov_b32_e32 v93, 0
	s_and_saveexec_b64 s[24:25], vcc
	global_load_dwordx2 v[92:93], v4, s[46:47]
	s_mov_b64 exec, s[24:25]
	s_branch .Lpi0_done_early

.Lpi0_done_early:
	s_mov_b32 s31, s30
